# attention active path: dropped s_nop 0 pads that no transcendental-result consumer needs (on v36)
# baseline (speedup 1.0000x reference)
; template <int DQK, bool MLA> ...
;     ...
;     auto substep = [&](f32x16& a, f32x16& b, int knext_ofs, int vofs, int h, int kafter_ofs) __attribute__((always_inline)) {
;         const LAS unsigned char* kb = lds + knext_ofs + r32 * KPITCH + hi * 16;
;         const LAS unsigned char* vb = lds + vofs + r32 * 144 + hi * 16 + h * 64;
;         u32x4 pw0, pw1; bf16x8 vf0[4], vf1[4], kr[3];
;         kr[0] = kp0; kr[1] = kp1;
;         float rs0 = rs_early;
;         __builtin_amdgcn_sched_barrier(0);
; #pragma unroll
;         for (int d0 = 0; d0 < KS; ++d0) {
;             if (d0 + 2 < KS) kr[(d0 + 2) % 3] = *(const LAS bf16x8*)(kb + (d0 + 2) * 32);
;             if (d0 == KS - 3) {
; #pragma unroll
;                 for (int d = 0; d < 4; ++d) vf0[d] = *(const LAS bf16x8*)(vb + d * 4608);
;             }
;             if (d0 == 0) { const f32x16 z16 = {0.f, 0.f, 0.f, 0.f, 0.f, 0.f, 0.f, 0.f, 0.f, 0.f, 0.f, 0.f, 0.f, 0.f, 0.f, 0.f};
;                 b = __builtin_amdgcn_mfma_f32_32x32x16_bf16(kr[0], qf[0], z16, 0, 0, 0); }
;             else b = __builtin_amdgcn_mfma_f32_32x32x16_bf16(kr[d0 % 3], qf[d0], b, 0, 0, 0);
; #pragma unroll
;             for (int e = 6 + (10 * d0) / KS; e < 6 + (10 * (d0 + 1)) / KS; ++e) {
;                 const float x = __builtin_amdgcn_exp2f(a[e]);
;                 a[e] = x;
;                 rs0 += x;
;                 if (e == 7)  { pw0.x = pk(a[0], a[1]); pw0.y = pk(a[2], a[3]);   pw0.z = pk(a[4], a[5]);   pw0.w = pk(a[6], a[7]); }
;                 if (e == 15) { pw1.x = pk(a[8], a[9]); pw1.y = pk(a[10], a[11]); pw1.z = pk(a[12], a[13]); pw1.w = pk(a[14], a[15]); }
;             }
;             __builtin_amdgcn_sched_barrier(0);
;         }
;         l_run += rs0;
;         float rs_n = 0.f;
; #pragma unroll
;         for (int kk = 0; kk < 2; ++kk) {
;             if (kk == 0) {
; #pragma unroll
;                 for (int d = 0; d < 4; ++d) vf1[d] = *(const LAS bf16x8*)(vb + d * 4608 + 32);
;             } else { const LAS unsigned char* ka = lds + kafter_ofs + r32 * KPITCH + hi * 16; kp0 = *(const LAS bf16x8*)(ka); kp1 = *(const LAS bf16x8*)(ka + 32); }
;             const bf16x8 pb = __builtin_bit_cast(bf16x8, kk ? pw1 : pw0);
; #pragma unroll
;             for (int d = 0; d < 4; ++d) {
;                 o[d] = __builtin_amdgcn_mfma_f32_32x32x16_bf16(kk ? vf1[d] : vf0[d], pb, o[d], 0, 0, 0);
.LBB0_1041:
	s_mov_b32 s72, s71
	s_mov_b32 s71, s34
	s_cmp_gt_u32 s68, s48
	s_cbranch_scc1 .Lattn_inact
	s_bitcmp1_b32 s68, 0
	s_cselect_b32 s34, s87, 0x12c00
	v_add_u32_e32 v193, s70, v183
	v_add_u32_e32 v208, s34, v175
	s_waitcnt lgkmcnt(1)
	v_mfma_f32_32x32x16_bf16 v[80:95], v[80:83], v[100:103], 0
	ds_read_b128 v[210:213], v193 offset:12864
	global_load_dwordx4 v[148:151], v[204:205], off
	global_load_dwordx4 v[152:155], v[206:207], off
	v_lshl_add_u64 v[204:205], v[204:205], 0, s[14:15]
	v_lshl_add_u64 v[206:207], v[206:207], 0, s[14:15]
	s_waitcnt lgkmcnt(1)
	v_mfma_f32_32x32x16_bf16 v[80:95], v[160:163], v[104:107], v[80:95]
	v_exp_f32_e32 v70, v70
	ds_read_b128 v[214:217], v193 offset:12896
	v_add_f32_e32 v186, v70, v186
	v_lshl_add_u64 v[234:235], s[26:27], 0, v[202:203]
	global_load_dwordx4 v[156:159], v[234:235], off
	v_lshl_add_u64 v[202:203], v[202:203], 0, s[0:1]
	s_waitcnt lgkmcnt(1)
	v_mfma_f32_32x32x16_bf16 v[80:95], v[210:213], v[108:111], v[80:95]
	ds_read_b128 v[160:163], v193 offset:12928
	v_exp_f32_e32 v71, v71
	v_cvt_pk_bf16_f32 v64, v64, v65
	v_cvt_pk_bf16_f32 v65, v66, v67
	v_cvt_pk_bf16_f32 v66, v68, v69
	v_cvt_pk_bf16_f32 v67, v70, v71
	v_add_f32_e32 v186, v71, v186
	s_waitcnt lgkmcnt(1)
	v_mfma_f32_32x32x16_bf16 v[80:95], v[214:217], v[112:115], v[80:95]
	ds_read_b128 v[68:71], v193 offset:12960
	v_lshl_add_u64 v[234:235], s[26:27], 0, v[190:191]
	v_add_co_u32_e32 v236, vcc, 0x1d204000, v234
	s_nop 1
	v_addc_co_u32_e32 v237, vcc, 0, v235, vcc
	global_load_dwordx4 v[164:167], v[236:237], off offset:2048
	v_exp_f32_e32 v194, v72
	s_nop 0
	v_add_f32_e32 v72, v194, v186
	s_waitcnt lgkmcnt(1)
	v_mfma_f32_32x32x16_bf16 v[80:95], v[160:163], v[116:119], v[80:95]
	v_exp_f32_e32 v186, v73
	ds_read_b128 v[210:213], v193 offset:12992
	v_add_f32_e32 v72, v186, v72
	v_add_co_u32_e32 v236, vcc, 0x1d206000, v234
	s_nop 1
	v_addc_co_u32_e32 v237, vcc, 0, v235, vcc
	global_load_dwordx4 v[168:171], v[236:237], off offset:2048
	s_waitcnt lgkmcnt(1)
	v_mfma_f32_32x32x16_bf16 v[80:95], v[68:71], v[120:123], v[80:95]
	s_and_saveexec_b64 s[34:35], s[4:5]
	s_cbranch_execz .Lattn_ld6_skip
	v_add_co_u32_e32 v236, vcc, 0x1d208000, v234
	s_nop 1
	v_addc_co_u32_e32 v237, vcc, 0, v235, vcc
	global_load_dwordx4 v[96:99], v[236:237], off offset:2048
.Lattn_ld6_skip:
	s_or_b64 exec, exec, s[34:35]
	ds_read_b128 v[160:163], v193 offset:13024
	v_exp_f32_e32 v195, v74
	s_nop 0
	v_add_f32_e32 v72, v195, v72
	v_lshl_add_u64 v[190:191], v[190:191], 0, s[20:21]
	s_waitcnt lgkmcnt(1)
	v_mfma_f32_32x32x16_bf16 v[80:95], v[210:213], v[124:127], v[80:95]
	ds_read_b128 v[68:71], v193 offset:13056
	s_waitcnt lgkmcnt(1)
	v_mfma_f32_32x32x16_bf16 v[80:95], v[160:163], v[128:131], v[80:95]
	v_exp_f32_e32 v196, v75
	ds_read_b128 v[210:213], v193 offset:13088
	v_add_f32_e32 v160, v196, v72
	s_waitcnt lgkmcnt(1)
	v_mfma_f32_32x32x16_bf16 v[80:95], v[68:71], v[136:139], v[80:95]
	ds_read_b128 v[72:75], v193 offset:13120
	v_exp_f32_e32 v76, v76
	s_nop 0
	v_add_f32_e32 v197, v76, v160
	ds_read_b128 v[68:71], v193 offset:13152
	ds_read_b128 v[160:163], v208
	ds_read_b128 v[214:217], v208 offset:4608
	ds_read_b128 v[218:221], v208 offset:9216
	ds_read_b128 v[222:225], v208 offset:13824
	s_waitcnt lgkmcnt(6)
	v_mfma_f32_32x32x16_bf16 v[80:95], v[210:213], v[144:147], v[80:95]
	v_exp_f32_e32 v77, v77
	s_nop 0
	v_add_f32_e32 v193, v77, v197
	s_waitcnt lgkmcnt(5)
	v_mfma_f32_32x32x16_bf16 v[80:95], v[72:75], v[132:135], v[80:95]
	v_exp_f32_e32 v72, v78
	s_nop 0
	v_add_f32_e32 v73, v72, v193
	s_waitcnt lgkmcnt(4)
	v_mfma_f32_32x32x16_bf16 v[80:95], v[68:71], v[140:143], v[80:95]
	v_exp_f32_e32 v71, v79
	v_cvt_pk_bf16_f32 v68, v194, v186
	v_cvt_pk_bf16_f32 v69, v195, v196
	v_cvt_pk_bf16_f32 v70, v76, v77
	v_add_f32_e32 v73, v71, v73
	v_cvt_pk_bf16_f32 v71, v72, v71
	s_waitcnt lgkmcnt(3)
	v_mfma_f32_32x32x16_bf16 v[48:63], v[160:163], v[64:67], v[48:63]
	v_add_f32_e32 v187, v187, v73
	ds_read_b128 v[72:75], v208 offset:32
	ds_read_b128 v[76:79], v208 offset:4640
	ds_read_b128 v[160:163], v208 offset:9248
	ds_read_b128 v[210:213], v208 offset:13856
	s_nop 1
	v_exp_f32_e32 v186, v80
	v_exp_f32_e32 v193, v81
	s_waitcnt lgkmcnt(6)
	v_mfma_f32_32x32x16_bf16 v[32:47], v[214:217], v[64:67], v[32:47]
	s_waitcnt lgkmcnt(5)
	v_mfma_f32_32x32x16_bf16 v[16:31], v[218:221], v[64:67], v[16:31]
	s_waitcnt lgkmcnt(4)
	v_mfma_f32_32x32x16_bf16 v[0:15], v[222:225], v[64:67], v[0:15]
	s_waitcnt lgkmcnt(3)
	v_mfma_f32_32x32x16_bf16 v[48:63], v[72:75], v[68:71], v[48:63]
	v_exp_f32_e32 v195, v82
	v_add_u32_e32 v194, s72, v183
	v_exp_f32_e32 v196, v83
	ds_read_b128 v[64:67], v194
	ds_read_b128 v[214:217], v194 offset:32
	v_exp_f32_e32 v84, v84
	v_add_f32_e32 v72, 0, v186
	v_exp_f32_e32 v85, v85
	s_waitcnt lgkmcnt(4)
	v_mfma_f32_32x32x16_bf16 v[32:47], v[76:79], v[68:71], v[32:47]
	v_add_f32_e32 v72, v193, v72
	v_add_f32_e32 v72, v195, v72
	v_add_f32_e32 v72, v196, v72
	v_add_f32_e32 v72, v84, v72
	v_add_f32_e32 v197, v85, v72
	s_waitcnt lgkmcnt(3)
; template <int DQK, bool MLA> ...
;     ...
;     auto substep = [&](f32x16& a, f32x16& b, int knext_ofs, int vofs, int h, int kafter_ofs) __attribute__((always_inline)) {
;         const LAS unsigned char* kb = lds + knext_ofs + r32 * KPITCH + hi * 16;
;         const LAS unsigned char* vb = lds + vofs + r32 * 144 + hi * 16 + h * 64;
;         u32x4 pw0, pw1; bf16x8 vf0[4], vf1[4], kr[3];
;         kr[0] = kp0; kr[1] = kp1;
;         float rs0 = rs_early;
;         __builtin_amdgcn_sched_barrier(0);
; #pragma unroll
;         for (int d0 = 0; d0 < KS; ++d0) {
;             if (d0 + 2 < KS) kr[(d0 + 2) % 3] = *(const LAS bf16x8*)(kb + (d0 + 2) * 32);
;             if (d0 == KS - 3) {
; #pragma unroll
;                 for (int d = 0; d < 4; ++d) vf0[d] = *(const LAS bf16x8*)(vb + d * 4608);
;             }
;             if (d0 == 0) { const f32x16 z16 = {0.f, 0.f, 0.f, 0.f, 0.f, 0.f, 0.f, 0.f, 0.f, 0.f, 0.f, 0.f, 0.f, 0.f, 0.f, 0.f};
;                 b = __builtin_amdgcn_mfma_f32_32x32x16_bf16(kr[0], qf[0], z16, 0, 0, 0); }
;             else b = __builtin_amdgcn_mfma_f32_32x32x16_bf16(kr[d0 % 3], qf[d0], b, 0, 0, 0);
; #pragma unroll
;             for (int e = 6 + (10 * d0) / KS; e < 6 + (10 * (d0 + 1)) / KS; ++e) {
;                 const float x = __builtin_amdgcn_exp2f(a[e]);
;                 a[e] = x;
;                 rs0 += x;
;                 if (e == 7)  { pw0.x = pk(a[0], a[1]); pw0.y = pk(a[2], a[3]);   pw0.z = pk(a[4], a[5]);   pw0.w = pk(a[6], a[7]); }
;                 if (e == 15) { pw1.x = pk(a[8], a[9]); pw1.y = pk(a[10], a[11]); pw1.z = pk(a[12], a[13]); pw1.w = pk(a[14], a[15]); }
;             }
;             __builtin_amdgcn_sched_barrier(0);
;         }
;         l_run += rs0;
;         float rs_n = 0.f;
; #pragma unroll
;         for (int kk = 0; kk < 2; ++kk) {
;             if (kk == 0) {
; #pragma unroll
;                 for (int d = 0; d < 4; ++d) vf1[d] = *(const LAS bf16x8*)(vb + d * 4608 + 32);
;             } else { const LAS unsigned char* ka = lds + kafter_ofs + r32 * KPITCH + hi * 16; kp0 = *(const LAS bf16x8*)(ka); kp1 = *(const LAS bf16x8*)(ka + 32); }
;             const bf16x8 pb = __builtin_bit_cast(bf16x8, kk ? pw1 : pw0);
; #pragma unroll
;             for (int d = 0; d < 4; ++d) {
;                 o[d] = __builtin_amdgcn_mfma_f32_32x32x16_bf16(kk ? vf1[d] : vf0[d], pb, o[d], 0, 0, 0);
	v_mfma_f32_32x32x16_bf16 v[16:31], v[160:163], v[68:71], v[16:31]
	s_waitcnt lgkmcnt(2)
	v_mfma_f32_32x32x16_bf16 v[0:15], v[210:213], v[68:71], v[0:15]
	s_waitcnt lgkmcnt(1)
	v_mfma_f32_32x32x16_bf16 v[64:79], v[64:67], v[100:103], 0
	ds_read_b128 v[80:83], v194 offset:64
	s_waitcnt lgkmcnt(1)
	v_mfma_f32_32x32x16_bf16 v[64:79], v[214:217], v[104:107], v[64:79]
	ds_read_b128 v[160:163], v194 offset:96
	v_exp_f32_e32 v86, v86
	s_nop 0
	v_add_f32_e32 v197, v86, v197
	s_waitcnt lgkmcnt(1)
	v_mfma_f32_32x32x16_bf16 v[64:79], v[80:83], v[108:111], v[64:79]
	ds_read_b128 v[210:213], v194 offset:128
	v_exp_f32_e32 v83, v87
	v_cvt_pk_bf16_f32 v80, v186, v193
	v_cvt_pk_bf16_f32 v81, v195, v196
	v_cvt_pk_bf16_f32 v82, v84, v85
	v_add_f32_e32 v197, v83, v197
	v_cvt_pk_bf16_f32 v83, v86, v83
	s_waitcnt lgkmcnt(1)
	v_mfma_f32_32x32x16_bf16 v[64:79], v[160:163], v[112:115], v[64:79]
	ds_read_b128 v[84:87], v194 offset:160
	v_exp_f32_e32 v186, v88
	s_nop 0
	v_add_f32_e32 v88, v186, v197
	s_waitcnt lgkmcnt(1)
	v_mfma_f32_32x32x16_bf16 v[64:79], v[210:213], v[116:119], v[64:79]
	ds_read_b128 v[160:163], v194 offset:192
	v_exp_f32_e32 v196, v89
	s_nop 0
	v_add_f32_e32 v88, v196, v88
	s_waitcnt lgkmcnt(1)
	v_mfma_f32_32x32x16_bf16 v[64:79], v[84:87], v[120:123], v[64:79]
	ds_read_b128 v[210:213], v194 offset:224
	v_exp_f32_e32 v226, v90
	s_nop 0
	v_add_f32_e32 v193, v226, v88
	s_waitcnt lgkmcnt(1)
	v_mfma_f32_32x32x16_bf16 v[64:79], v[160:163], v[124:127], v[64:79]
	ds_read_b128 v[84:87], v194 offset:256
	s_waitcnt lgkmcnt(1)
	v_mfma_f32_32x32x16_bf16 v[64:79], v[210:213], v[128:131], v[64:79]
	ds_read_b128 v[160:163], v194 offset:288
	v_exp_f32_e32 v195, v91
	s_waitcnt lgkmcnt(1)
	v_mfma_f32_32x32x16_bf16 v[64:79], v[84:87], v[136:139], v[64:79]
	ds_read_b128 v[88:91], v194 offset:320
	v_exp_f32_e32 v197, v92
	ds_read_b128 v[84:87], v194 offset:352
	ds_read_b128 v[210:213], v208 offset:64
	ds_read_b128 v[214:217], v208 offset:4672
	ds_read_b128 v[218:221], v208 offset:9280
	ds_read_b128 v[222:225], v208 offset:13888
	s_waitcnt lgkmcnt(6)
	v_mfma_f32_32x32x16_bf16 v[64:79], v[160:163], v[144:147], v[64:79]
	v_exp_f32_e32 v209, v93
	s_waitcnt lgkmcnt(5)
	v_mfma_f32_32x32x16_bf16 v[64:79], v[88:91], v[132:135], v[64:79]
	v_exp_f32_e32 v227, v94
	s_waitcnt lgkmcnt(4)
	v_mfma_f32_32x32x16_bf16 v[64:79], v[84:87], v[140:143], v[64:79]
	v_exp_f32_e32 v229, v95
	v_cvt_pk_bf16_f32 v84, v186, v196
	v_cvt_pk_bf16_f32 v85, v226, v195
	v_cvt_pk_bf16_f32 v86, v197, v209
	v_cvt_pk_bf16_f32 v87, v227, v229
	s_waitcnt lgkmcnt(3)
	v_mfma_f32_32x32x16_bf16 v[48:63], v[210:213], v[80:83], v[48:63]
	s_add_i32 s98, s68, 1
	s_bitcmp1_b32 s98, 0
	s_cselect_b32 s98, 0x4800, 0
	v_add_u32_e32 v230, s71, v172
	v_add_u32_e32 v231, s71, v174
	v_add_u32_e32 v232, s71, v184
	v_add_u32_e32 v233, s98, v173
	s_waitcnt vmcnt(4)
	ds_write_b128 v230, v[148:151]
	v_exp_f32_e32 v64, v64
	v_exp_f32_e32 v65, v65
	s_waitcnt lgkmcnt(3)
	v_mfma_f32_32x32x16_bf16 v[32:47], v[214:217], v[80:83], v[32:47]
	ds_read_b128 v[88:91], v208 offset:96
	ds_read_b128 v[92:95], v208 offset:4704
	ds_read_b128 v[210:213], v208 offset:9312
	ds_read_b128 v[214:217], v208 offset:13920
	s_waitcnt lgkmcnt(6)
	v_mfma_f32_32x32x16_bf16 v[16:31], v[218:221], v[80:83], v[16:31]
	s_waitcnt vmcnt(3)
	ds_write_b128 v231, v[152:155]
	s_waitcnt lgkmcnt(6)
	v_mfma_f32_32x32x16_bf16 v[0:15], v[222:225], v[80:83], v[0:15]
	v_exp_f32_e32 v66, v66
	s_waitcnt vmcnt(2)
	ds_write_b128 v232, v[156:159] offset:256
	s_waitcnt lgkmcnt(5)
	v_mfma_f32_32x32x16_bf16 v[48:63], v[88:91], v[84:87], v[48:63]
	v_exp_f32_e32 v67, v67
	ds_read_b128 v[80:83], v194 offset:12800
	ds_read_b128 v[160:163], v194 offset:12832
	v_exp_f32_e32 v68, v68
	v_mov_b32_e32 v194, v64
	v_exp_f32_e32 v69, v69
	v_pk_add_f32 v[88:89], v[194:195], v[192:193]
	v_mov_b32_e32 v196, v65
	s_waitcnt lgkmcnt(6)
	v_mfma_f32_32x32x16_bf16 v[32:47], v[92:95], v[84:87], v[32:47]
	v_add_f32_e64 v88, v196, v88
	v_add_f32_e64 v89, v197, v89
	v_mov_b32_e32 v208, v66
	v_add_f32_e64 v88, v208, v88
	v_add_f32_e64 v89, v209, v89
	v_mov_b32_e32 v226, v67
	v_pk_add_f32 v[88:89], v[226:227], v[88:89]
	v_mov_b32_e32 v228, v68
	v_pk_add_f32 v[88:89], v[228:229], v[88:89]
	s_waitcnt vmcnt(1)
	ds_write_b128 v233, v[164:167]
	s_waitcnt lgkmcnt(6)
	v_mfma_f32_32x32x16_bf16 v[16:31], v[210:213], v[84:87], v[16:31]
	v_mov_b32_e32 v186, v69
	v_add_f32_e64 v186, v186, v88
	v_add_f32_e64 v187, v187, v89
	s_waitcnt vmcnt(0)
	ds_write_b128 v233, v[168:171] offset:8192
	s_waitcnt lgkmcnt(6)
	v_mfma_f32_32x32x16_bf16 v[0:15], v[214:217], v[84:87], v[0:15]
	s_add_i32 s68, s68, 1
	s_add_i32 s73, s71, 0
	s_bitcmp1_b32 s68, 0
	s_cselect_b64 s[34:35], -1, 0
	s_and_b64 s[66:67], s[34:35], exec
	s_cselect_b32 s66, 0x4800, 0
	s_and_saveexec_b64 s[66:67], s[4:5]
	ds_write_b128 v233, v[96:99] offset:16384
	s_or_b64 exec, exec, s[66:67]
	s_branch .Lattn_wtail
